# v054 minus the per-tile conditional s_setprio block and one scalar copy, adjacent lgkmcnt/vmcnt waits merged
# speedup vs baseline: 1.0088x; 1.0088x over previous
; __device__ __forceinline__ void finishSM(f32x16& p0, f32x16& p1, float alpha, float& l_reg, bf16x8& pa0, bf16x8& pa1, bf16x8& pa2, bf16x8& pa3) {
; #pragma unroll
;   for (int r = 0; r < 16; ++r) p1[r] = __builtin_amdgcn_exp2f(p1[r]);
;   float ps = 0;
; #pragma unroll
;   for (int r = 0; r < 16; ++r) ps += p0[r];
; #pragma unroll
;   for (int r = 0; r < 16; ++r) ps += p1[r];
;   { auto rr = __builtin_amdgcn_permlane32_swap(__float_as_uint(ps), __float_as_uint(ps), false, false);
;     ps = __uint_as_float(rr[0]) + __uint_as_float(rr[1]); }
;   l_reg = l_reg * alpha + ps;
;     ...
;   PK4(p0, 0, pa0); PK4(p0, 8, pa1); PK4(p1, 0, pa2); PK4(p1, 8, pa3);
;     ...
; }
; template <int NQ> __device__ __forceinline__ void qkt(f32x16& p0, f32x16& p1, const char* Ks, const bf16x8* qr, int r32, int hi, int kcolB) {
;   p0 = f32x16{}; p1 = f32x16{};
; #pragma unroll
;   for (int d0 = 0; d0 < NQ; ++d0) { const int cb = kcolB + (d0 * 16 + hi * 8) * 2;
;     bf16x8 b0 = *reinterpret_cast<const bf16x8*>(Ks + KSWZ(r32, cb));
;     bf16x8 b1 = *reinterpret_cast<const bf16x8*>(Ks + KSWZ(32 + r32, cb));
;     p0 = __builtin_amdgcn_mfma_f32_32x32x16_bf16(b0, qr[d0], p0, 0, 0, 0);
;     p1 = __builtin_amdgcn_mfma_f32_32x32x16_bf16(b1, qr[d0], p1, 0, 0, 0); }
; }
; __device__ __forceinline__ void qkt0(f32x16& p0, f32x16& p1, const char* Ks, const char* Qs, int r32, int hi, int kcolB, const f32x16& init) {
; #pragma unroll
;   for (int d0 = 0; d0 < 4; ++d0) { const int cb = kcolB + (d0 * 16 + hi * 8) * 2;
;     bf16x8 b0 = *reinterpret_cast<const bf16x8*>(Ks + KSWZ(r32, cb));
;     bf16x8 b1 = *reinterpret_cast<const bf16x8*>(Ks + KSWZ(32 + r32, cb));
;     bf16x8 qf = *reinterpret_cast<const bf16x8*>(Qs + r32 * 128 + (((2 * d0 + hi) ^ (r32 & 7)) << 4));
;     if (d0 == 0) { p0 = __builtin_amdgcn_mfma_f32_32x32x16_bf16(b0, qf, init, 0, 0, 0); p1 = __builtin_amdgcn_mfma_f32_32x32x16_bf16(b1, qf, init, 0, 0, 0); }
;     else { p0 = __builtin_amdgcn_mfma_f32_32x32x16_bf16(b0, qf, p0, 0, 0, 0); p1 = __builtin_amdgcn_mfma_f32_32x32x16_bf16(b1, qf, p1, 0, 0, 0); } }
; }
.LBB0_215:
	v_add_u32_e32 v112, s59, v193
	v_add_u32_e32 v116, s59, v194
	ds_read_b128 v[112:115], v112 offset:16384
	ds_read_b128 v[202:205], v181
	ds_read_b128 v[206:209], v180
	ds_read_b128 v[210:213], v116 offset:16384
	v_exp_f32_e32 v234, v96
	v_add_f32_e32 v96, 0, v161
	s_waitcnt lgkmcnt(2)
	v_mfma_f32_32x32x16_bf16 v[128:143], v[112:115], v[202:205], v[80:95]
	v_add_u32_e32 v112, s59, v197
	v_add_u32_e32 v113, s59, v195
	v_add_f32_e32 v96, v163, v96
	ds_read_b128 v[214:217], v112 offset:16384
	ds_read_b128 v[218:221], v113 offset:16384
	v_add_f32_e32 v96, v159, v96
	v_add_f32_e32 v96, v162, v96
	v_add_f32_e32 v96, v157, v96
	s_waitcnt lgkmcnt(2)
	v_mfma_f32_32x32x16_bf16 v[112:127], v[210:213], v[202:205], v[80:95]
	v_add_f32_e32 v96, v160, v96
	v_add_f32_e32 v96, v156, v96
	v_add_f32_e32 v96, v158, v96
	v_add_f32_e32 v96, v153, v96
	v_add_f32_e32 v96, v155, v96
	v_add_f32_e32 v96, v151, v96
	v_add_f32_e32 v96, v154, v96
	s_waitcnt lgkmcnt(0)
	v_mfma_f32_32x32x16_bf16 v[128:143], v[218:221], v[206:209], v[128:143]
	v_add_f32_e32 v96, v149, v96
	v_add_u32_e32 v201, s59, v199
	v_add_u32_e32 v210, s59, v196
	v_exp_f32_e32 v235, v97
	v_add_f32_e32 v96, v152, v96
	ds_read_b128 v[202:205], v201 offset:16384
	ds_read_b128 v[210:213], v210 offset:16384
	ds_read_b128 v[222:225], v179
	ds_read_b128 v[226:229], v178
	v_exp_f32_e32 v236, v98
	v_mfma_f32_32x32x16_bf16 v[112:127], v[214:217], v[206:209], v[112:127]
	v_add_f32_e32 v96, v148, v96
	v_exp_f32_e32 v237, v99
	v_add_f32_e32 v96, v150, v96
	v_exp_f32_e32 v238, v100
	v_add_f32_e32 v96, v234, v96
	v_exp_f32_e32 v239, v101
	v_add_f32_e32 v96, v235, v96
	v_exp_f32_e32 v206, v102
	s_waitcnt lgkmcnt(1)
	v_mfma_f32_32x32x16_bf16 v[128:143], v[210:213], v[222:225], v[128:143]
	v_add_f32_e32 v96, v236, v96
	v_exp_f32_e32 v207, v103
	v_add_f32_e32 v96, v237, v96
	v_add_u32_e32 v201, s59, v200
	v_add_u32_e32 v230, s59, v198
	v_exp_f32_e32 v208, v104
	v_add_f32_e32 v96, v238, v96
	v_mfma_f32_32x32x16_bf16 v[112:127], v[202:205], v[222:225], v[112:127]
	ds_read_b128 v[218:221], v201 offset:16384
	ds_read_b128 v[230:233], v230 offset:16384
	v_exp_f32_e32 v209, v105
	v_add_f32_e32 v96, v239, v96
	v_exp_f32_e32 v214, v106
	v_add_f32_e32 v96, v206, v96
	v_exp_f32_e32 v215, v107
	v_add_f32_e32 v96, v207, v96
	v_exp_f32_e32 v216, v108
	v_add_f32_e32 v96, v208, v96
	v_exp_f32_e32 v210, v109
	v_add_f32_e32 v96, v209, v96
	v_exp_f32_e32 v211, v110
	s_waitcnt lgkmcnt(0)
	v_mfma_f32_32x32x16_bf16 v[128:143], v[230:233], v[226:229], v[128:143]
	v_add_f32_e32 v96, v214, v96
	v_exp_f32_e32 v111, v111
	v_add_f32_e32 v96, v215, v96
	v_add_f32_e32 v96, v216, v96
	v_add_f32_e32 v96, v210, v96
	v_add_f32_e32 v96, v211, v96
	v_add_f32_e32 v201, v111, v96
	v_mfma_f32_32x32x16_bf16 v[112:127], v[218:221], v[226:229], v[112:127]
	v_mov_b32_e32 v202, v201
	s_nop 1
	v_permlane32_swap_b32_e32 v201, v202
	v_cvt_pk_bf16_f32 v96, v161, v163
	v_cvt_pk_bf16_f32 v97, v159, v162
	v_cvt_pk_bf16_f32 v98, v157, v160
	v_cvt_pk_bf16_f32 v99, v156, v158
	v_cvt_pk_bf16_f32 v100, v153, v155
	v_cvt_pk_bf16_f32 v101, v151, v154
	v_cvt_pk_bf16_f32 v102, v149, v152
	v_cvt_pk_bf16_f32 v103, v148, v150
	v_cvt_pk_bf16_f32 v104, v234, v235
	v_cvt_pk_bf16_f32 v105, v236, v237
	v_cvt_pk_bf16_f32 v106, v238, v239
	v_cvt_pk_bf16_f32 v107, v206, v207
	v_cvt_pk_bf16_f32 v108, v208, v209
	v_cvt_pk_bf16_f32 v109, v214, v215
	v_cvt_pk_bf16_f32 v110, v216, v210
	v_cvt_pk_bf16_f32 v111, v211, v111
	v_permlane32_swap_b32_e32 v96, v98
	v_permlane32_swap_b32_e32 v97, v99
	v_permlane32_swap_b32_e32 v100, v102
	v_permlane32_swap_b32_e32 v101, v103
	v_permlane32_swap_b32_e32 v104, v106
	v_permlane32_swap_b32_e32 v105, v107
	v_permlane32_swap_b32_e32 v108, v110
	v_permlane32_swap_b32_e32 v109, v111
	v_add_u32_e32 v203, s36, v175
	ds_read_b64_tr_b16 v[148:149], v203 offset:0
	ds_read_b64_tr_b16 v[150:151], v203 offset:0x800
	ds_read_b64_tr_b16 v[152:153], v203 offset:0x1000
	ds_read_b64_tr_b16 v[154:155], v203 offset:0x1800
	ds_read_b64_tr_b16 v[156:157], v203 offset:0x2000
	ds_read_b64_tr_b16 v[158:159], v203 offset:0x2800
	ds_read_b64_tr_b16 v[160:161], v203 offset:0x3000
	ds_read_b64_tr_b16 v[162:163], v203 offset:0x3800
	s_add_i32 s34, s58, 1
	s_waitcnt lgkmcnt(0)
; __device__ __forceinline__ void pv_d0(f32x16* o, int vb, bf16x8 pa0, bf16x8 pa1, bf16x8 pa2, bf16x8 pa3) {
;   s16x4 la[4], ha[4];
;   rd8<0>(la, ha, vb); WAITDEP(0, la, ha); mma4(o[0], la, ha, pa0, pa1, pa2, pa3);
;   rd8<1>(la, ha, vb); WAITDEP(0, la, ha); mma4(o[1], la, ha, pa0, pa1, pa2, pa3);
;   rd8<2>(la, ha, vb); WAITDEP(0, la, ha); mma4(o[2], la, ha, pa0, pa1, pa2, pa3);
;   rd8<3>(la, ha, vb); WAITDEP(0, la, ha); mma4(o[3], la, ha, pa0, pa1, pa2, pa3);
; }
; template <int MODE>
; __device__ __forceinline__ void attn_unit(bf16r* P0, const bf16r* __restrict__ PKV, int rowbase, int seqL, int h, int blk, float lam,
;                                           const float* __restrict__ subg, const float* __restrict__ tsrc, char* lds) {
;   constexpr int NQ = (MODE == 0) ? 4 : 8;
;   int tid_ = threadIdx.x; asm volatile("" : "+v"(tid_));
;   const int tid = tid_, wid = __builtin_amdgcn_readfirstlane(tid >> 6), lane = tid & 63, r32 = lane & 31, hi = lane >> 5;
;   float* ws = (float*)(lds + OFF_WS) + wid * 64; float* li_l = ws; float* al_l = ws + 32;
;   float* tb = (float*)(lds + OFF_TB);
;   int qrow, kcolB, tbase, NT, colbase, gr = 0, rs = 0, qc = 0, cmap = 0;
;   float bL = 0.f, bR = 0.f;
;   if constexpr (MODE == 0) {
;     cmap = wid >> 2; qrow = blk * 128 + (wid & 3) * 32; kcolB = cmap * 128; tbase = 0; NT = seqL / KVBLK; colbase = h * 128;
;     bL = tsrc[15 * 8 + h] * LOG2E; bR = tsrc[31 * 8 + h] * LOG2E;
;     { const int rel = tid - 256, n = rel < 0 ? -rel : rel;
;       int bk = n < 8 ? n : min(15, 8 + (31 - __clz((n * n) >> 6))); if (rel > 0) bk += 16;
;       tb[tid] = tsrc[bk * 8 + h] * LOG2E; }
;   } else {
;     const int rows = seqL / 64; qrow = blk * 256 + wid * 32; kcolB = 0; colbase = 1024 + h * 128; NT = 12;
;     const int rs0 = min(max(blk * 4 - 4, 0), rows - 8); tbase = min(rs0, rows - 12);
;     gr = blk * 4 + (wid >> 1); rs = min(max(gr - 4, 0), rows - 8); qc = (wid & 1) * 32 + r32;
;     for (int i = tid; i < 15 * 128; i += 512) { const int dr = i >> 7, dc = (i & 127) - 48; tb[i] = (dc >= 0 && dc < 31) ? tsrc[(h * 15 + dr) * 31 + dc] * LOG2E : 0.f; }
;   }
;   const bf16r* Qw = P0 + (size_t)(rowbase + qrow + r32) * LD + colbase + (MODE == 0 ? cmap * 64 : 0) + hi * 8;
;   const bf16r* Kh = PKV + (size_t)rowbase * LD + h * 128; const bf16r* Vh = Kh + 1024;
;   float m_reg = -1e30f, l_reg = 0; f32x16 o[4] = {};
	s_add_i32 s60, s37, 0
	v_mfma_f32_32x32x16_bf16 v[64:79], v[96:99], v[148:151], v[64:79]
	ds_read_b64_tr_b16 v[148:149], v203 offset:0x200
	ds_read_b64_tr_b16 v[150:151], v203 offset:0xa00
	ds_read_b64_tr_b16 v[204:205], v203 offset:0x1200
	ds_read_b64_tr_b16 v[206:207], v203 offset:0x1a00
	ds_read_b64_tr_b16 v[208:209], v203 offset:0x2200
	ds_read_b64_tr_b16 v[210:211], v203 offset:0x2a00
	ds_read_b64_tr_b16 v[212:213], v203 offset:0x3200
	v_mfma_f32_32x32x16_bf16 v[64:79], v[100:103], v[152:155], v[64:79]
	ds_read_b64_tr_b16 v[214:215], v203 offset:0x3a00
	s_min_i32 s34, s34, s39
	s_waitcnt lgkmcnt(0)
	s_cmp_ge_i32 s34, s56
	s_cselect_b32 s35, s57, 0
	s_add_i32 s35, s35, s34
	s_lshl_b32 s34, s35, 6
	v_mfma_f32_32x32x16_bf16 v[64:79], v[104:107], v[156:159], v[64:79]
	v_mfma_f32_32x32x16_bf16 v[48:63], v[96:99], v[148:151], v[48:63]
	ds_read_b64_tr_b16 v[148:149], v203 offset:0x400
	ds_read_b64_tr_b16 v[150:151], v203 offset:0xc00
	ds_read_b64_tr_b16 v[152:153], v203 offset:0x1400
	ds_read_b64_tr_b16 v[154:155], v203 offset:0x1c00
	v_mfma_f32_32x32x16_bf16 v[64:79], v[108:111], v[160:163], v[64:79]
	ds_read_b64_tr_b16 v[160:161], v203 offset:0x2400
	ds_read_b64_tr_b16 v[162:163], v203 offset:0x2c00
	v_mfma_f32_32x32x16_bf16 v[48:63], v[100:103], v[204:207], v[48:63]
	ds_read_b64_tr_b16 v[204:205], v203 offset:0x3400
	ds_read_b64_tr_b16 v[206:207], v203 offset:0x3c00
	s_nop 0
	s_waitcnt lgkmcnt(0)
	ds_read_b64_tr_b16 v[216:217], v203 offset:0x600
	ds_read_b64_tr_b16 v[218:219], v203 offset:0xe00
	s_nop 0
	v_mfma_f32_32x32x16_bf16 v[32:47], v[96:99], v[148:151], v[32:47]
	s_lshl_b32 s98, s34, 12
	s_add_u32 s98, s30, s98
	s_addc_u32 s99, s31, 0
	v_mfma_f32_32x32x16_bf16 v[48:63], v[104:107], v[208:211], v[48:63]
	ds_read_b64_tr_b16 v[208:209], v203 offset:0x1600
	ds_read_b64_tr_b16 v[210:211], v203 offset:0x1e00
	ds_read_b64_tr_b16 v[220:221], v203 offset:0x2600
	ds_read_b64_tr_b16 v[222:223], v203 offset:0x2e00
	ds_read_b64_tr_b16 v[224:225], v203 offset:0x3600
	ds_read_b64_tr_b16 v[226:227], v203 offset:0x3e00
	v_mfma_f32_32x32x16_bf16 v[32:47], v[100:103], v[152:155], v[32:47]
	s_waitcnt vmcnt(0) lgkmcnt(0)
	global_load_dwordx4 v[156:159], v252, s[98:99] offset:2048
	s_nop 0
	global_load_dwordx4 v[148:151], v252, s[98:99]
	v_add_u32_e32 v203, s60, v183
	v_mfma_f32_32x32x16_bf16 v[32:47], v[104:107], v[160:163], v[32:47]
	global_load_dwordx4 v[160:163], v253, s[98:99] offset:2048
	s_nop 0
	global_load_dwordx4 v[152:155], v253, s[98:99]
	ds_write_b128 v203, v[6:9]
	v_add_u32_e32 v6, s60, v189
	ds_write_b128 v6, v[144:147]
	v_add_u32_e32 v6, s60, v190
	ds_write_b128 v6, v[2:5] offset:16384
	v_add_u32_e32 v2, s60, v191
	v_mfma_f32_32x32x16_bf16 v[16:31], v[96:99], v[216:219], v[16:31]
	ds_write_b128 v2, v[10:13] offset:16384
	v_max_f32_e32 v2, v128, v129
	v_max3_f32 v2, v2, v130, v131
	v_max3_f32 v2, v2, v132, v133
	v_max3_f32 v2, v2, v134, v135
	v_mfma_f32_32x32x16_bf16 v[16:31], v[100:103], v[208:211], v[16:31]
	v_max3_f32 v2, v2, v136, v137
	v_max3_f32 v2, v2, v138, v139
	v_max3_f32 v2, v2, v140, v141
	v_max3_f32 v2, v2, v142, v143
	v_max3_f32 v2, v2, v112, v113
	v_max3_f32 v2, v2, v114, v115
	v_max3_f32 v2, v2, v116, v117
	v_mfma_f32_32x32x16_bf16 v[16:31], v[104:107], v[220:223], v[16:31]
	v_max3_f32 v2, v2, v118, v119
	v_max3_f32 v2, v2, v120, v121
	v_max3_f32 v2, v2, v122, v123
	v_max3_f32 v2, v2, v124, v125
	v_max3_f32 v2, v2, v126, v127
	v_mov_b32_e32 v3, v2
	s_nop 1
	v_permlane32_swap_b32_e32 v2, v3
	v_mfma_f32_32x32x16_bf16 v[48:63], v[108:111], v[212:215], v[48:63]
	v_max_f32_e32 v2, v2, v3
	v_cmp_ge_f32_e32 vcc, s49, v2
	s_cmp_eq_u64 vcc, exec
	v_mov_b32_e32 v203, 1.0
	v_mfma_f32_32x32x16_bf16 v[32:47], v[108:111], v[204:207], v[32:47]
	v_mfma_f32_32x32x16_bf16 v[16:31], v[108:111], v[224:227], v[16:31]
	s_cbranch_scc1 .LBB0_220
	s_branch .LBB0_229

; __device__ __forceinline__ void finishSM(f32x16& p0, f32x16& p1, float alpha, float& l_reg, bf16x8& pa0, bf16x8& pa1, bf16x8& pa2, bf16x8& pa3) {
; #pragma unroll
;   for (int r = 0; r < 16; ++r) p1[r] = __builtin_amdgcn_exp2f(p1[r]);
;   float ps = 0;
; #pragma unroll
;   for (int r = 0; r < 16; ++r) ps += p0[r];
; #pragma unroll
;   for (int r = 0; r < 16; ++r) ps += p1[r];
;   { auto rr = __builtin_amdgcn_permlane32_swap(__float_as_uint(ps), __float_as_uint(ps), false, false);
;     ps = __uint_as_float(rr[0]) + __uint_as_float(rr[1]); }
;   l_reg = l_reg * alpha + ps;
;     ...
;   PK4(p0, 0, pa0); PK4(p0, 8, pa1); PK4(p1, 0, pa2); PK4(p1, 8, pa3);
;     ...
; }
; template <int NQ> __device__ __forceinline__ void qkt(f32x16& p0, f32x16& p1, const char* Ks, const bf16x8* qr, int r32, int hi, int kcolB) {
;   p0 = f32x16{}; p1 = f32x16{};
; #pragma unroll
;   for (int d0 = 0; d0 < NQ; ++d0) { const int cb = kcolB + (d0 * 16 + hi * 8) * 2;
;     bf16x8 b0 = *reinterpret_cast<const bf16x8*>(Ks + KSWZ(r32, cb));
;     bf16x8 b1 = *reinterpret_cast<const bf16x8*>(Ks + KSWZ(32 + r32, cb));
;     p0 = __builtin_amdgcn_mfma_f32_32x32x16_bf16(b0, qr[d0], p0, 0, 0, 0);
;     p1 = __builtin_amdgcn_mfma_f32_32x32x16_bf16(b1, qr[d0], p1, 0, 0, 0); }
; }
; __device__ __forceinline__ void qkt0(f32x16& p0, f32x16& p1, const char* Ks, const char* Qs, int r32, int hi, int kcolB, const f32x16& init) {
; #pragma unroll
;   for (int d0 = 0; d0 < 4; ++d0) { const int cb = kcolB + (d0 * 16 + hi * 8) * 2;
;     bf16x8 b0 = *reinterpret_cast<const bf16x8*>(Ks + KSWZ(r32, cb));
;     bf16x8 b1 = *reinterpret_cast<const bf16x8*>(Ks + KSWZ(32 + r32, cb));
;     bf16x8 qf = *reinterpret_cast<const bf16x8*>(Qs + r32 * 128 + (((2 * d0 + hi) ^ (r32 & 7)) << 4));
;     if (d0 == 0) { p0 = __builtin_amdgcn_mfma_f32_32x32x16_bf16(b0, qf, init, 0, 0, 0); p1 = __builtin_amdgcn_mfma_f32_32x32x16_bf16(b1, qf, init, 0, 0, 0); }
;     else { p0 = __builtin_amdgcn_mfma_f32_32x32x16_bf16(b0, qf, p0, 0, 0, 0); p1 = __builtin_amdgcn_mfma_f32_32x32x16_bf16(b1, qf, p1, 0, 0, 0); } }
; }
.LBB0_222:
	v_exp_f32_e32 v224, v128
	v_exp_f32_e32 v225, v129
	v_exp_f32_e32 v226, v130
	v_exp_f32_e32 v227, v131
	v_exp_f32_e32 v228, v132
	v_exp_f32_e32 v229, v133
	v_exp_f32_e32 v230, v134
	v_exp_f32_e32 v231, v135
	v_exp_f32_e32 v232, v136
	v_exp_f32_e32 v233, v137
	v_exp_f32_e32 v234, v138
	v_exp_f32_e32 v235, v139
	v_exp_f32_e32 v236, v140
	v_exp_f32_e32 v237, v141
	v_exp_f32_e32 v238, v142
	v_exp_f32_e32 v239, v143
	v_add_u32_e32 v2, s60, v193
	ds_read_b128 v[2:5], v2 offset:16384
	ds_read_b128 v[6:9], v181
	v_add_u32_e32 v96, s60, v194
	ds_read_b128 v[10:13], v180
	v_add_u32_e32 v97, s60, v195
	v_add_u32_e32 v208, s60, v199
	s_waitcnt lgkmcnt(1)
	v_mfma_f32_32x32x16_bf16 v[128:143], v[2:5], v[6:9], v[80:95]
	ds_read_b128 v[2:5], v96 offset:16384
	v_add_u32_e32 v96, s60, v197
	ds_read_b128 v[144:147], v96 offset:16384
	ds_read_b128 v[204:207], v97 offset:16384
	v_add_u32_e32 v209, s60, v196
	v_exp_f32_e32 v240, v114
	v_exp_f32_e32 v241, v115
	v_exp_f32_e32 v242, v116
	s_waitcnt lgkmcnt(0)
	v_mfma_f32_32x32x16_bf16 v[128:143], v[204:207], v[10:13], v[128:143]
	v_exp_f32_e32 v206, v112
	v_exp_f32_e32 v207, v113
	v_exp_f32_e32 v243, v117
	v_exp_f32_e32 v244, v118
	v_add_u32_e32 v216, s60, v200
	v_add_u32_e32 v220, s60, v198
	v_mfma_f32_32x32x16_bf16 v[96:111], v[2:5], v[6:9], v[80:95]
	ds_read_b128 v[2:5], v208 offset:16384
	ds_read_b128 v[6:9], v209 offset:16384
	ds_read_b128 v[208:211], v179
	ds_read_b128 v[212:215], v178
	ds_read_b128 v[216:219], v216 offset:16384
	ds_read_b128 v[220:223], v220 offset:16384
	v_cvt_pk_bf16_f32 v116, v224, v225
	v_cvt_pk_bf16_f32 v117, v226, v227
	v_cvt_pk_bf16_f32 v118, v228, v229
	s_nop 0
	v_permlane32_swap_b32_e32 v116, v118
	v_mfma_f32_32x32x16_bf16 v[96:111], v[144:147], v[10:13], v[96:111]
	v_exp_f32_e32 v10, v119
	v_exp_f32_e32 v11, v120
	v_exp_f32_e32 v12, v121
	v_exp_f32_e32 v13, v122
	v_exp_f32_e32 v144, v123
	v_exp_f32_e32 v145, v124
	v_exp_f32_e32 v146, v125
	s_waitcnt lgkmcnt(3)
	v_mfma_f32_32x32x16_bf16 v[128:143], v[6:9], v[208:211], v[128:143]
	v_add_f32_e32 v8, 0, v224
	v_add_f32_e32 v8, v225, v8
	v_add_f32_e32 v8, v226, v8
	v_add_f32_e32 v8, v227, v8
	v_add_f32_e32 v8, v228, v8
	v_exp_f32_e32 v6, v126
	v_exp_f32_e32 v7, v127
	v_mfma_f32_32x32x16_bf16 v[96:111], v[2:5], v[208:211], v[96:111]
	v_add_f32_e32 v2, v229, v8
	v_add_f32_e32 v2, v230, v2
	v_add_f32_e32 v2, v231, v2
	v_add_f32_e32 v2, v232, v2
	v_add_f32_e32 v2, v233, v2
	v_add_f32_e32 v2, v234, v2
	v_add_f32_e32 v2, v235, v2
	v_add_f32_e32 v2, v236, v2
	v_add_f32_e32 v2, v237, v2
	v_add_f32_e32 v2, v238, v2
	v_add_f32_e32 v2, v239, v2
	v_add_f32_e32 v2, v206, v2
	v_add_f32_e32 v2, v207, v2
	v_add_f32_e32 v2, v240, v2
	v_add_f32_e32 v2, v241, v2
	v_add_f32_e32 v2, v242, v2
	v_add_f32_e32 v2, v243, v2
	v_add_f32_e32 v2, v244, v2
	v_add_f32_e32 v2, v10, v2
	v_add_f32_e32 v2, v11, v2
	v_add_f32_e32 v2, v12, v2
	s_waitcnt lgkmcnt(0)
	v_mfma_f32_32x32x16_bf16 v[128:143], v[220:223], v[212:215], v[128:143]
	v_add_f32_e32 v2, v13, v2
	v_add_f32_e32 v2, v144, v2
	v_add_f32_e32 v2, v145, v2
	v_add_f32_e32 v2, v146, v2
	v_add_f32_e32 v2, v6, v2
	v_add_f32_e32 v204, v7, v2
	v_mov_b32_e32 v205, v204
	v_mfma_f32_32x32x16_bf16 v[96:111], v[216:219], v[212:215], v[96:111]
	v_cvt_pk_bf16_f32 v119, v230, v231
	v_cvt_pk_bf16_f32 v112, v232, v233
	v_cvt_pk_bf16_f32 v113, v234, v235
	v_cvt_pk_bf16_f32 v114, v236, v237
	v_cvt_pk_bf16_f32 v115, v238, v239
	s_nop 0
	v_permlane32_swap_b32_e32 v204, v205
	v_permlane32_swap_b32_e32 v112, v114
	v_permlane32_swap_b32_e32 v113, v115
	v_cvt_pk_bf16_f32 v120, v206, v207
	v_cvt_pk_bf16_f32 v121, v240, v241
	v_cvt_pk_bf16_f32 v122, v242, v243
	v_cvt_pk_bf16_f32 v123, v244, v10
	v_cvt_pk_bf16_f32 v124, v11, v12
	v_cvt_pk_bf16_f32 v125, v13, v144
	v_cvt_pk_bf16_f32 v126, v145, v146
	v_cvt_pk_bf16_f32 v127, v6, v7
	v_permlane32_swap_b32_e32 v117, v119
	v_permlane32_swap_b32_e32 v120, v122
	v_permlane32_swap_b32_e32 v121, v123
	v_permlane32_swap_b32_e32 v124, v126
	v_permlane32_swap_b32_e32 v125, v127
	v_add_u32_e32 v230, s59, v175
	ds_read_b64_tr_b16 v[2:3], v230 offset:0
	ds_read_b64_tr_b16 v[4:5], v230 offset:0x800
	ds_read_b64_tr_b16 v[6:7], v230 offset:0x1000
	ds_read_b64_tr_b16 v[8:9], v230 offset:0x1800
	ds_read_b64_tr_b16 v[10:11], v230 offset:0x2000
	ds_read_b64_tr_b16 v[12:13], v230 offset:0x2800
	ds_read_b64_tr_b16 v[144:145], v230 offset:0x3000
	ds_read_b64_tr_b16 v[146:147], v230 offset:0x3800
	s_add_i32 s58, s58, 2
	s_waitcnt lgkmcnt(0)
; __device__ __forceinline__ void pv_d0(f32x16* o, int vb, bf16x8 pa0, bf16x8 pa1, bf16x8 pa2, bf16x8 pa3) {
;   s16x4 la[4], ha[4];
;   rd8<0>(la, ha, vb); WAITDEP(0, la, ha); mma4(o[0], la, ha, pa0, pa1, pa2, pa3);
;   rd8<1>(la, ha, vb); WAITDEP(0, la, ha); mma4(o[1], la, ha, pa0, pa1, pa2, pa3);
;   rd8<2>(la, ha, vb); WAITDEP(0, la, ha); mma4(o[2], la, ha, pa0, pa1, pa2, pa3);
;   rd8<3>(la, ha, vb); WAITDEP(0, la, ha); mma4(o[3], la, ha, pa0, pa1, pa2, pa3);
; }
; template <int MODE>
; __device__ __forceinline__ void attn_unit(bf16r* P0, const bf16r* __restrict__ PKV, int rowbase, int seqL, int h, int blk, float lam,
;                                           const float* __restrict__ subg, const float* __restrict__ tsrc, char* lds) {
;   constexpr int NQ = (MODE == 0) ? 4 : 8;
;   int tid_ = threadIdx.x; asm volatile("" : "+v"(tid_));
;   const int tid = tid_, wid = __builtin_amdgcn_readfirstlane(tid >> 6), lane = tid & 63, r32 = lane & 31, hi = lane >> 5;
;   float* ws = (float*)(lds + OFF_WS) + wid * 64; float* li_l = ws; float* al_l = ws + 32;
;   float* tb = (float*)(lds + OFF_TB);
;   int qrow, kcolB, tbase, NT, colbase, gr = 0, rs = 0, qc = 0, cmap = 0;
;   float bL = 0.f, bR = 0.f;
;   if constexpr (MODE == 0) {
;     cmap = wid >> 2; qrow = blk * 128 + (wid & 3) * 32; kcolB = cmap * 128; tbase = 0; NT = seqL / KVBLK; colbase = h * 128;
;     bL = tsrc[15 * 8 + h] * LOG2E; bR = tsrc[31 * 8 + h] * LOG2E;
;     { const int rel = tid - 256, n = rel < 0 ? -rel : rel;
;       int bk = n < 8 ? n : min(15, 8 + (31 - __clz((n * n) >> 6))); if (rel > 0) bk += 16;
;       tb[tid] = tsrc[bk * 8 + h] * LOG2E; }
;   } else {
;     const int rows = seqL / 64; qrow = blk * 256 + wid * 32; kcolB = 0; colbase = 1024 + h * 128; NT = 12;
;     const int rs0 = min(max(blk * 4 - 4, 0), rows - 8); tbase = min(rs0, rows - 12);
;     gr = blk * 4 + (wid >> 1); rs = min(max(gr - 4, 0), rows - 8); qc = (wid & 1) * 32 + r32;
;     for (int i = tid; i < 15 * 128; i += 512) { const int dr = i >> 7, dc = (i & 127) - 48; tb[i] = (dc >= 0 && dc < 31) ? tsrc[(h * 15 + dr) * 31 + dc] * LOG2E : 0.f; }
;   }
;   const bf16r* Qw = P0 + (size_t)(rowbase + qrow + r32) * LD + colbase + (MODE == 0 ? cmap * 64 : 0) + hi * 8;
;   const bf16r* Kh = PKV + (size_t)rowbase * LD + h * 128; const bf16r* Vh = Kh + 1024;
;   float m_reg = -1e30f, l_reg = 0; f32x16 o[4] = {};
	s_add_i32 s34, s36, 0
	v_mfma_f32_32x32x16_bf16 v[64:79], v[116:119], v[2:5], v[64:79]
	ds_read_b64_tr_b16 v[2:3], v230 offset:0x200
	ds_read_b64_tr_b16 v[4:5], v230 offset:0xa00
	ds_read_b64_tr_b16 v[206:207], v230 offset:0x1200
	ds_read_b64_tr_b16 v[208:209], v230 offset:0x1a00
	ds_read_b64_tr_b16 v[210:211], v230 offset:0x2200
	ds_read_b64_tr_b16 v[212:213], v230 offset:0x2a00
	ds_read_b64_tr_b16 v[214:215], v230 offset:0x3200
	v_mfma_f32_32x32x16_bf16 v[64:79], v[112:115], v[6:9], v[64:79]
	ds_read_b64_tr_b16 v[216:217], v230 offset:0x3a00
	s_min_i32 s35, s58, s39
	s_waitcnt lgkmcnt(0)
	s_cmp_ge_i32 s35, s56
	s_cselect_b32 s60, s57, 0
	s_add_i32 s60, s60, s35
	s_lshl_b32 s35, s60, 6
	v_mfma_f32_32x32x16_bf16 v[48:63], v[116:119], v[2:5], v[48:63]
	ds_read_b64_tr_b16 v[2:3], v230 offset:0x400
	ds_read_b64_tr_b16 v[4:5], v230 offset:0xc00
	ds_read_b64_tr_b16 v[6:7], v230 offset:0x1400
	ds_read_b64_tr_b16 v[8:9], v230 offset:0x1c00
	v_mfma_f32_32x32x16_bf16 v[64:79], v[120:123], v[10:13], v[64:79]
	ds_read_b64_tr_b16 v[10:11], v230 offset:0x2400
	ds_read_b64_tr_b16 v[12:13], v230 offset:0x2c00
	v_mfma_f32_32x32x16_bf16 v[48:63], v[112:115], v[206:209], v[48:63]
	ds_read_b64_tr_b16 v[206:207], v230 offset:0x3400
	ds_read_b64_tr_b16 v[208:209], v230 offset:0x3c00
	s_nop 0
	s_waitcnt lgkmcnt(0)
	ds_read_b64_tr_b16 v[218:219], v230 offset:0x600
	ds_read_b64_tr_b16 v[220:221], v230 offset:0xe00
	s_nop 0
	v_mfma_f32_32x32x16_bf16 v[32:47], v[116:119], v[2:5], v[32:47]
	s_lshl_b32 s98, s35, 12
	s_add_u32 s98, s30, s98
	s_addc_u32 s99, s31, 0
	v_mfma_f32_32x32x16_bf16 v[48:63], v[120:123], v[210:213], v[48:63]
	ds_read_b64_tr_b16 v[210:211], v230 offset:0x1600
	ds_read_b64_tr_b16 v[212:213], v230 offset:0x1e00
	ds_read_b64_tr_b16 v[222:223], v230 offset:0x2600
	ds_read_b64_tr_b16 v[224:225], v230 offset:0x2e00
	ds_read_b64_tr_b16 v[226:227], v230 offset:0x3600
	ds_read_b64_tr_b16 v[228:229], v230 offset:0x3e00
	v_mfma_f32_32x32x16_bf16 v[32:47], v[112:115], v[6:9], v[32:47]
	s_waitcnt vmcnt(0) lgkmcnt(0)
	v_mfma_f32_32x32x16_bf16 v[48:63], v[124:127], v[214:217], v[48:63]
	global_load_dwordx4 v[6:9], v252, s[98:99] offset:2048
	s_nop 0
	global_load_dwordx4 v[2:5], v252, s[98:99]
	v_mfma_f32_32x32x16_bf16 v[64:79], v[124:127], v[144:147], v[64:79]
	v_mfma_f32_32x32x16_bf16 v[32:47], v[120:123], v[10:13], v[32:47]
	global_load_dwordx4 v[144:147], v253, s[98:99] offset:2048
	global_load_dwordx4 v[10:13], v253, s[98:99]
	v_add_u32_e32 v214, s34, v183
	ds_write_b128 v214, v[156:159]
	v_add_u32_e32 v156, s34, v189
	ds_write_b128 v156, v[160:163]
	v_add_u32_e32 v156, s34, v190
	ds_write_b128 v156, v[148:151] offset:16384
	v_mfma_f32_32x32x16_bf16 v[16:31], v[116:119], v[218:221], v[16:31]
	v_add_u32_e32 v148, s34, v191
	ds_write_b128 v148, v[152:155] offset:16384
	v_max_f32_e32 v148, v128, v129
	v_max3_f32 v148, v148, v130, v131
	v_max3_f32 v148, v148, v132, v133
	v_mfma_f32_32x32x16_bf16 v[16:31], v[112:115], v[210:213], v[16:31]
	v_max3_f32 v116, v148, v134, v135
	v_max3_f32 v116, v116, v136, v137
	v_max3_f32 v116, v116, v138, v139
	v_max3_f32 v116, v116, v140, v141
	v_max3_f32 v116, v116, v142, v143
	v_max3_f32 v116, v116, v96, v97
	v_max3_f32 v116, v116, v98, v99
	v_mfma_f32_32x32x16_bf16 v[16:31], v[120:123], v[222:225], v[16:31]
	v_max3_f32 v112, v116, v100, v101
	v_max3_f32 v112, v112, v102, v103
	v_max3_f32 v112, v112, v104, v105
	v_max3_f32 v112, v112, v106, v107
	v_max3_f32 v112, v112, v108, v109
	v_max3_f32 v112, v112, v110, v111
	v_mov_b32_e32 v113, v112
	v_mfma_f32_32x32x16_bf16 v[32:47], v[124:127], v[206:209], v[32:47]
	s_nop 0
	v_permlane32_swap_b32_e32 v112, v113
	v_max_f32_e32 v113, v112, v113
	v_cmp_ge_f32_e32 vcc, s49, v113
	s_cmp_eq_u64 vcc, exec
	v_mfma_f32_32x32x16_bf16 v[16:31], v[124:127], v[226:229], v[16:31]
	v_mov_b32_e32 v112, 1.0
	s_cbranch_scc1 .LBB0_227
	s_branch .LBB0_230
